# hyena short-conv halo loads: the masked previous-element load stays in flight across the next-element load (one wait for both), 12 sites
# speedup vs baseline: 1.0009x; 1.0009x over previous
.LBB0_1614:
	s_or_b64 exec, exec, s[0:1]
	s_waitcnt lgkmcnt(0)
	s_barrier
	ds_read_b32 v0, v1 offset:58392
	s_movk_i32 s0, 0x1ff
	s_waitcnt lgkmcnt(0)
	v_cmp_lt_i32_e32 vcc, s0, v0
	v_readfirstlane_b32 s16, v0
	s_mov_b64 s[0:1], -1
	s_cbranch_vccnz .LBB0_1609
	v_readlane_b32 s36, v253, 34
	v_readlane_b32 s48, v253, 46
	v_readlane_b32 s49, v253, 47
	v_mov_b32_e32 v30, v196
	s_mov_b64 s[8:9], s[62:63]
	s_mov_b64 s[18:19], s[62:63]
	s_mov_b64 s[0:1], s[48:49]
	v_readlane_b32 s2, v255, 14
	s_add_u32 s4, s0, s2
	v_readlane_b32 s2, v255, 15
	v_readlane_b32 s50, v253, 48
	v_readlane_b32 s51, v253, 49
	v_readlane_b32 s3, v255, 16
	s_addc_u32 s12, s1, 0
	s_mov_b64 s[0:1], s[50:51]
	s_lshl_b64 s[2:3], s[2:3], 2
	s_add_u32 s2, s0, s2
	s_addc_u32 s3, s1, s3
	s_ashr_i32 s17, s16, 31
	s_lshl_b64 s[0:1], s[16:17], 2
	s_add_u32 s14, s4, s0
	s_addc_u32 s15, s12, s1
	v_mov_b32_e32 v0, 0x3000
	s_barrier
	global_load_dword v18, v207, s[14:15] offset:2048
	global_load_dword v16, v0, s[14:15]
	v_ashrrev_i32_e32 v0, 31, v30
	v_lshrrev_b32_e32 v0, 25, v0
	s_add_u32 s2, s2, s0
	v_add_u32_e32 v0, v30, v0
	s_addc_u32 s3, s3, s1
	v_ashrrev_i32_e32 v17, 7, v0
	v_and_b32_e32 v0, 0xffffff80, v0
	v_mov_b64_e32 v[8:9], s[16:17]
	s_movk_i32 s24, 0x600
	v_sub_u32_e32 v0, v30, v0
	s_add_u32 s8, s8, 0x8e80000
	v_mad_i64_i32 v[8:9], s[12:13], v17, s24, v[8:9]
	v_lshlrev_b32_e32 v2, 3, v0
	s_addc_u32 s9, s9, 0
	v_lshlrev_b64 v[8:9], 11, v[8:9]
	v_lshl_add_u64 v[8:9], s[8:9], 0, v[8:9]
	v_ashrrev_i32_e32 v3, 31, v2
	v_lshl_add_u64 v[22:23], v[2:3], 1, v[8:9]
	global_load_dword v19, v1, s[14:15]
	global_load_dword v20, v1, s[2:3]
	global_load_dwordx4 v[8:11], v[22:23], off
	v_readlane_b32 s37, v253, 35
	v_cmp_lt_i32_e64 s[36:37], 0, v0
	v_mov_b32_e32 v13, 0
	v_mov_b32_e32 v15, 0
	v_readlane_b32 s38, v253, 36
	v_readlane_b32 s39, v253, 37
	v_readlane_b32 s40, v253, 38
	v_readlane_b32 s41, v253, 39
	v_readlane_b32 s42, v253, 40
	v_readlane_b32 s43, v253, 41
	v_readlane_b32 s44, v253, 42
	v_readlane_b32 s45, v253, 43
	v_readlane_b32 s46, v253, 44
	v_readlane_b32 s47, v253, 45
	s_and_saveexec_b64 s[12:13], s[36:37]
	s_cbranch_execz .LBB0_1617
	global_load_ushort v251, v[22:23], off offset:-2

.LBB0_1619:
	s_or_b64 exec, exec, s[12:13]
	s_waitcnt vmcnt(0)
	v_lshlrev_b32_e32 v250, 16, v251
	v_cndmask_b32_e64 v15, v15, v250, s[36:37]
	s_waitcnt vmcnt(0)
	v_lshlrev_b32_e32 v27, 16, v9
	v_and_b32_e32 v28, 0xffff0000, v8
	v_and_b32_e32 v23, 0xffff0000, v9
	v_lshlrev_b32_e32 v26, 16, v8
	v_mov_b32_e32 v32, v28
	v_mov_b32_e32 v33, v27
	v_mov_b32_e32 v8, v26
	v_mov_b32_e32 v9, v28
	v_mov_b32_e32 v0, v19
	v_pk_mul_f32 v[32:33], v[18:19], v[32:33] op_sel_hi:[0,1]
	v_mov_b32_e32 v14, v23
	v_mov_b32_e32 v22, v27
	v_pk_fma_f32 v[8:9], v[0:1], v[8:9], v[32:33] op_sel_hi:[0,1,1]
	v_pk_mul_f32 v[14:15], v[18:19], v[14:15]
	v_lshlrev_b32_e32 v29, 16, v10
	v_pk_fma_f32 v[8:9], v[16:17], v[22:23], v[8:9] op_sel_hi:[0,1,1]
	v_pk_fma_f32 v[14:15], v[18:19], v[26:27], v[14:15] op_sel:[0,0,1] op_sel_hi:[1,1,0]
	v_pk_add_f32 v[8:9], v[20:21], v[8:9] op_sel_hi:[0,1]
	v_pk_fma_f32 v[14:15], v[16:17], v[28:29], v[14:15] op_sel_hi:[0,1,1]
	v_pk_add_f32 v[14:15], v[20:21], v[14:15] op_sel_hi:[0,1]
	v_and_b32_sdwa v21, v8, v208 dst_sel:DWORD dst_unused:UNUSED_PAD src0_sel:WORD_1 src1_sel:DWORD
	v_and_b32_sdwa v12, v9, v208 dst_sel:DWORD dst_unused:UNUSED_PAD src0_sel:WORD_1 src1_sel:DWORD
	v_add3_u32 v8, v8, v21, s34
	v_and_b32_sdwa v21, v14, v208 dst_sel:DWORD dst_unused:UNUSED_PAD src0_sel:WORD_1 src1_sel:DWORD
	v_lshlrev_b32_e32 v25, 16, v11
	v_add3_u32 v9, v9, v12, s34
	v_and_b32_e32 v8, 0xffff0000, v8
	v_and_b32_sdwa v12, v15, v208 dst_sel:DWORD dst_unused:UNUSED_PAD src0_sel:WORD_1 src1_sel:DWORD
	v_add3_u32 v14, v14, v21, s34
	v_and_b32_e32 v11, 0xffff0000, v11
	v_and_b32_e32 v10, 0xffff0000, v10
	v_add3_u32 v12, v15, v12, s34
	v_or_b32_sdwa v8, v14, v8 dst_sel:DWORD dst_unused:UNUSED_PAD src0_sel:WORD_1 src1_sel:DWORD
	v_pk_mov_b32 v[14:15], v[22:23], v[10:11] op_sel:[1,0]
	v_mov_b32_e32 v22, v29
	v_mov_b32_e32 v23, v25
	v_pk_mul_f32 v[22:23], v[18:19], v[22:23] op_sel_hi:[0,1]
	v_pk_fma_f32 v[14:15], v[0:1], v[14:15], v[22:23] op_sel_hi:[0,1,1]
	v_mov_b32_e32 v28, v11
	v_and_b32_e32 v12, 0xffff0000, v12
	v_mov_b32_e32 v24, v10
	v_pk_fma_f32 v[14:15], v[16:17], v[10:11], v[14:15] op_sel_hi:[0,1,1]
	v_pk_mul_f32 v[10:11], v[18:19], v[28:29]
	v_or_b32_sdwa v9, v12, v9 dst_sel:DWORD dst_unused:UNUSED_PAD src0_sel:DWORD src1_sel:WORD_1
	v_pk_fma_f32 v[10:11], v[18:19], v[24:25], v[10:11] op_sel:[0,0,1] op_sel_hi:[1,1,0]
	v_mov_b32_e32 v12, v25
	v_pk_fma_f32 v[10:11], v[16:17], v[12:13], v[10:11] op_sel_hi:[0,1,1]
	v_pk_add_f32 v[14:15], v[20:21], v[14:15] op_sel_hi:[0,1]
	v_pk_add_f32 v[10:11], v[20:21], v[10:11] op_sel_hi:[0,1]
	v_and_b32_sdwa v12, v14, v208 dst_sel:DWORD dst_unused:UNUSED_PAD src0_sel:WORD_1 src1_sel:DWORD
	v_and_b32_sdwa v13, v11, v208 dst_sel:DWORD dst_unused:UNUSED_PAD src0_sel:WORD_1 src1_sel:DWORD
	v_and_b32_sdwa v0, v15, v208 dst_sel:DWORD dst_unused:UNUSED_PAD src0_sel:WORD_1 src1_sel:DWORD
	v_add3_u32 v12, v14, v12, s34
	v_and_b32_sdwa v14, v10, v208 dst_sel:DWORD dst_unused:UNUSED_PAD src0_sel:WORD_1 src1_sel:DWORD
	v_add3_u32 v11, v11, v13, s34
	v_add3_u32 v0, v15, v0, s34
	v_add3_u32 v10, v10, v14, s34
	v_and_b32_e32 v11, 0xffff0000, v11
	v_and_b32_e32 v10, 0xffff0000, v10
	v_or_b32_sdwa v11, v11, v0 dst_sel:DWORD dst_unused:UNUSED_PAD src0_sel:DWORD src1_sel:WORD_1
	v_mul_lo_u32 v0, v17, s25
	v_or_b32_sdwa v10, v10, v12 dst_sel:DWORD dst_unused:UNUSED_PAD src0_sel:DWORD src1_sel:WORD_1
	v_lshl_add_u32 v114, v2, 1, v0
	ds_write_b128 v114, v[8:11] offset:41280
	v_add_u32_e32 v8, 0x100, v30
	v_ashrrev_i32_e32 v0, 31, v8
	v_lshrrev_b32_e32 v0, 25, v0
	v_add_u32_e32 v9, v8, v0
	v_ashrrev_i32_e32 v0, 7, v9
	v_and_b32_e32 v9, 0xffffff80, v9
	v_sub_u32_e32 v21, v8, v9
	v_mov_b64_e32 v[8:9], s[16:17]
	v_mad_i64_i32 v[8:9], s[12:13], v0, s24, v[8:9]
	v_lshlrev_b32_e32 v12, 3, v21
	v_lshlrev_b64 v[8:9], 11, v[8:9]
	v_lshl_add_u64 v[8:9], s[8:9], 0, v[8:9]
	v_ashrrev_i32_e32 v13, 31, v12
	v_lshl_add_u64 v[14:15], v[12:13], 1, v[8:9]
	global_load_dwordx4 v[8:11], v[14:15], off
	v_cmp_lt_i32_e64 s[40:41], 0, v21
	v_mov_b32_e32 v23, 0
	v_mov_b32_e32 v25, 0
	s_and_saveexec_b64 s[12:13], s[40:41]
	s_cbranch_execz .LBB0_1621
	global_load_ushort v251, v[14:15], off offset:-2

.LBB0_1623:
	s_or_b64 exec, exec, s[12:13]
	s_waitcnt vmcnt(0)
	v_lshlrev_b32_e32 v250, 16, v251
	v_cndmask_b32_e64 v25, v25, v250, s[40:41]
	s_waitcnt vmcnt(0)
	v_lshlrev_b32_e32 v37, 16, v9
	v_and_b32_e32 v38, 0xffff0000, v8
	v_mov_b32_e32 v28, v18
	v_mov_b32_e32 v29, v18
	v_and_b32_e32 v33, 0xffff0000, v9
	v_lshlrev_b32_e32 v36, 16, v8
	v_mov_b32_e32 v40, v38
	v_mov_b32_e32 v41, v37
	v_mov_b32_e32 v26, v19
	v_mov_b32_e32 v27, v19
	v_mov_b32_e32 v8, v36
	v_mov_b32_e32 v9, v38
	v_pk_mul_f32 v[40:41], v[28:29], v[40:41]
	v_mov_b32_e32 v24, v33
	v_mad_i64_i32 v[14:15], s[12:13], v17, s24, 0
	v_mov_b32_e32 v17, v16
	v_mov_b32_e32 v32, v37
	v_pk_fma_f32 v[8:9], v[26:27], v[8:9], v[40:41]
	v_pk_mul_f32 v[24:25], v[18:19], v[24:25]
	v_mov_b32_e32 v21, v20
	v_lshlrev_b32_e32 v39, 16, v10
	v_pk_fma_f32 v[8:9], v[16:17], v[32:33], v[8:9]
	v_pk_fma_f32 v[24:25], v[18:19], v[36:37], v[24:25] op_sel:[0,0,1] op_sel_hi:[1,1,0]
	v_pk_add_f32 v[8:9], v[20:21], v[8:9]
	v_pk_fma_f32 v[24:25], v[16:17], v[38:39], v[24:25]
	v_and_b32_sdwa v31, v8, v208 dst_sel:DWORD dst_unused:UNUSED_PAD src0_sel:WORD_1 src1_sel:DWORD
	v_pk_add_f32 v[24:25], v[20:21], v[24:25]
	v_and_b32_sdwa v22, v9, v208 dst_sel:DWORD dst_unused:UNUSED_PAD src0_sel:WORD_1 src1_sel:DWORD
	v_add3_u32 v8, v8, v31, s34
	v_and_b32_sdwa v31, v24, v208 dst_sel:DWORD dst_unused:UNUSED_PAD src0_sel:WORD_1 src1_sel:DWORD
	v_lshlrev_b32_e32 v35, 16, v11
	v_add3_u32 v9, v9, v22, s34
	v_and_b32_e32 v8, 0xffff0000, v8
	v_and_b32_sdwa v22, v25, v208 dst_sel:DWORD dst_unused:UNUSED_PAD src0_sel:WORD_1 src1_sel:DWORD
	v_add3_u32 v24, v24, v31, s34
	v_and_b32_e32 v11, 0xffff0000, v11
	v_and_b32_e32 v10, 0xffff0000, v10
	v_add3_u32 v22, v25, v22, s34
	v_or_b32_sdwa v8, v24, v8 dst_sel:DWORD dst_unused:UNUSED_PAD src0_sel:WORD_1 src1_sel:DWORD
	v_pk_mov_b32 v[24:25], v[32:33], v[10:11] op_sel:[1,0]
	v_mov_b32_e32 v32, v39
	v_mov_b32_e32 v33, v35
	v_pk_mul_f32 v[28:29], v[28:29], v[32:33]
	v_mov_b32_e32 v38, v11
	v_pk_fma_f32 v[24:25], v[26:27], v[24:25], v[28:29]
	v_and_b32_e32 v22, 0xffff0000, v22
	v_mov_b32_e32 v34, v10
	v_pk_fma_f32 v[24:25], v[16:17], v[10:11], v[24:25]
	v_pk_mul_f32 v[10:11], v[18:19], v[38:39]
	v_or_b32_sdwa v9, v22, v9 dst_sel:DWORD dst_unused:UNUSED_PAD src0_sel:DWORD src1_sel:WORD_1
	v_pk_fma_f32 v[10:11], v[18:19], v[34:35], v[10:11] op_sel:[0,0,1] op_sel_hi:[1,1,0]
	v_mov_b32_e32 v22, v35
	v_pk_fma_f32 v[10:11], v[16:17], v[22:23], v[10:11]
	v_pk_add_f32 v[24:25], v[20:21], v[24:25]
	v_pk_add_f32 v[10:11], v[20:21], v[10:11]
	v_and_b32_sdwa v16, v25, v208 dst_sel:DWORD dst_unused:UNUSED_PAD src0_sel:WORD_1 src1_sel:DWORD
	v_and_b32_sdwa v18, v11, v208 dst_sel:DWORD dst_unused:UNUSED_PAD src0_sel:WORD_1 src1_sel:DWORD
	v_and_b32_sdwa v19, v10, v208 dst_sel:DWORD dst_unused:UNUSED_PAD src0_sel:WORD_1 src1_sel:DWORD
	v_add3_u32 v11, v11, v18, s34
	v_and_b32_sdwa v17, v24, v208 dst_sel:DWORD dst_unused:UNUSED_PAD src0_sel:WORD_1 src1_sel:DWORD
	v_add3_u32 v16, v25, v16, s34
	v_add3_u32 v10, v10, v19, s34
	v_and_b32_e32 v11, 0xffff0000, v11
	v_add3_u32 v17, v24, v17, s34
	v_and_b32_e32 v10, 0xffff0000, v10
	v_or_b32_sdwa v11, v11, v16 dst_sel:DWORD dst_unused:UNUSED_PAD src0_sel:DWORD src1_sel:WORD_1
	v_mul_lo_u32 v16, v0, s25
	v_or_b32_sdwa v10, v10, v17 dst_sel:DWORD dst_unused:UNUSED_PAD src0_sel:DWORD src1_sel:WORD_1
	v_lshl_add_u32 v115, v12, 1, v16
	ds_write_b128 v115, v[8:11] offset:41280
	s_add_i32 s12, s16, 0x400
	v_mov_b32_e32 v8, 0x2000
	s_ashr_i32 s13, s12, 31
	global_load_dword v17, v207, s[14:15]
	global_load_dword v16, v8, s[14:15] offset:2048
	v_mov_b32_e32 v8, 0x4000
	global_load_dword v18, v8, s[14:15]
	global_load_dword v20, v207, s[2:3]
	v_lshl_add_u64 v[8:9], v[14:15], 0, s[12:13]
	v_lshlrev_b64 v[8:9], 11, v[8:9]
	v_lshl_add_u64 v[8:9], s[8:9], 0, v[8:9]
	v_lshl_add_u64 v[22:23], v[2:3], 1, v[8:9]
	global_load_dwordx4 v[8:11], v[22:23], off
	v_mov_b32_e32 v25, 0
	v_mov_b32_e32 v27, 0
	s_and_saveexec_b64 s[20:21], s[36:37]
	s_cbranch_execz .LBB0_1625
	global_load_ushort v251, v[22:23], off offset:-2

.LBB0_1627:
	s_or_b64 exec, exec, s[20:21]
	s_waitcnt vmcnt(0)
	v_lshlrev_b32_e32 v250, 16, v251
	v_cndmask_b32_e64 v27, v27, v250, s[36:37]
	s_waitcnt vmcnt(0)
	v_lshlrev_b32_e32 v35, 16, v9
	v_and_b32_e32 v36, 0xffff0000, v8
	v_and_b32_e32 v29, 0xffff0000, v9
	v_lshlrev_b32_e32 v34, 16, v8
	v_mov_b32_e32 v38, v36
	v_mov_b32_e32 v39, v35
	v_mad_i64_i32 v[22:23], s[20:21], v0, s24, 0
	v_mov_b32_e32 v8, v34
	v_mov_b32_e32 v9, v36
	v_mov_b32_e32 v0, v17
	v_pk_mul_f32 v[38:39], v[16:17], v[38:39] op_sel_hi:[0,1]
	v_mov_b32_e32 v26, v29
	v_mov_b32_e32 v28, v35
	v_pk_fma_f32 v[8:9], v[0:1], v[8:9], v[38:39] op_sel_hi:[0,1,1]
	v_pk_mul_f32 v[26:27], v[16:17], v[26:27]
	v_lshlrev_b32_e32 v37, 16, v10
	v_pk_fma_f32 v[8:9], v[18:19], v[28:29], v[8:9] op_sel_hi:[0,1,1]
	v_pk_fma_f32 v[26:27], v[16:17], v[34:35], v[26:27] op_sel:[0,0,1] op_sel_hi:[1,1,0]
	v_pk_add_f32 v[8:9], v[20:21], v[8:9] op_sel_hi:[0,1]
	v_pk_fma_f32 v[26:27], v[18:19], v[36:37], v[26:27] op_sel_hi:[0,1,1]
	v_pk_add_f32 v[26:27], v[20:21], v[26:27] op_sel_hi:[0,1]
	v_and_b32_sdwa v19, v9, v208 dst_sel:DWORD dst_unused:UNUSED_PAD src0_sel:WORD_1 src1_sel:DWORD
	v_and_b32_sdwa v21, v8, v208 dst_sel:DWORD dst_unused:UNUSED_PAD src0_sel:WORD_1 src1_sel:DWORD
	v_lshlrev_b32_e32 v33, 16, v11
	v_add3_u32 v9, v9, v19, s34
	v_add3_u32 v8, v8, v21, s34
	v_and_b32_sdwa v19, v27, v208 dst_sel:DWORD dst_unused:UNUSED_PAD src0_sel:WORD_1 src1_sel:DWORD
	v_and_b32_sdwa v21, v26, v208 dst_sel:DWORD dst_unused:UNUSED_PAD src0_sel:WORD_1 src1_sel:DWORD
	v_and_b32_e32 v11, 0xffff0000, v11
	v_and_b32_e32 v10, 0xffff0000, v10
	v_add3_u32 v19, v27, v19, s34
	v_add3_u32 v21, v26, v21, s34
	v_pk_mov_b32 v[26:27], v[28:29], v[10:11] op_sel:[1,0]
	v_mov_b32_e32 v28, v37
	v_mov_b32_e32 v29, v33
	v_pk_mul_f32 v[28:29], v[16:17], v[28:29] op_sel_hi:[0,1]
	v_and_b32_e32 v19, 0xffff0000, v19
	v_pk_fma_f32 v[26:27], v[0:1], v[26:27], v[28:29] op_sel_hi:[0,1,1]
	v_mov_b32_e32 v36, v11
	v_mov_b32_e32 v32, v10
	v_pk_fma_f32 v[26:27], v[18:19], v[10:11], v[26:27] op_sel_hi:[0,1,1]
	v_pk_mul_f32 v[10:11], v[16:17], v[36:37]
	v_mov_b32_e32 v24, v33
	v_pk_fma_f32 v[10:11], v[16:17], v[32:33], v[10:11] op_sel:[0,0,1] op_sel_hi:[1,1,0]
	v_and_b32_e32 v8, 0xffff0000, v8
	v_pk_fma_f32 v[10:11], v[18:19], v[24:25], v[10:11] op_sel_hi:[0,1,1]
	v_pk_add_f32 v[10:11], v[20:21], v[10:11] op_sel_hi:[0,1]
	v_or_b32_sdwa v8, v21, v8 dst_sel:DWORD dst_unused:UNUSED_PAD src0_sel:WORD_1 src1_sel:DWORD
	v_pk_add_f32 v[26:27], v[20:21], v[26:27] op_sel_hi:[0,1]
	v_and_b32_sdwa v21, v11, v208 dst_sel:DWORD dst_unused:UNUSED_PAD src0_sel:WORD_1 src1_sel:DWORD
	v_and_b32_sdwa v24, v10, v208 dst_sel:DWORD dst_unused:UNUSED_PAD src0_sel:WORD_1 src1_sel:DWORD
	v_or_b32_sdwa v9, v19, v9 dst_sel:DWORD dst_unused:UNUSED_PAD src0_sel:DWORD src1_sel:WORD_1
	v_and_b32_sdwa v0, v27, v208 dst_sel:DWORD dst_unused:UNUSED_PAD src0_sel:WORD_1 src1_sel:DWORD
	v_and_b32_sdwa v19, v26, v208 dst_sel:DWORD dst_unused:UNUSED_PAD src0_sel:WORD_1 src1_sel:DWORD
	v_add3_u32 v11, v11, v21, s34
	v_add3_u32 v10, v10, v24, s34
	v_add3_u32 v19, v26, v19, s34
	v_add3_u32 v0, v27, v0, s34
	v_and_b32_e32 v11, 0xffff0000, v11
	v_and_b32_e32 v10, 0xffff0000, v10
	v_or_b32_sdwa v11, v11, v0 dst_sel:DWORD dst_unused:UNUSED_PAD src0_sel:DWORD src1_sel:WORD_1
	v_or_b32_sdwa v10, v10, v19 dst_sel:DWORD dst_unused:UNUSED_PAD src0_sel:DWORD src1_sel:WORD_1
	ds_write_b128 v114, v[8:11] offset:33024
	v_lshl_add_u64 v[8:9], v[22:23], 0, s[12:13]
	v_lshlrev_b64 v[8:9], 11, v[8:9]
	v_lshl_add_u64 v[8:9], s[8:9], 0, v[8:9]
	v_lshl_add_u64 v[24:25], v[12:13], 1, v[8:9]
	global_load_dwordx4 v[8:11], v[24:25], off
	v_mov_b32_e32 v27, 0
	v_mov_b32_e32 v29, 0
	s_and_saveexec_b64 s[12:13], s[40:41]
	s_cbranch_execz .LBB0_1629
	global_load_ushort v251, v[24:25], off offset:-2

.LBB0_1631:
	s_or_b64 exec, exec, s[12:13]
	s_waitcnt vmcnt(0)
	v_lshlrev_b32_e32 v250, 16, v251
	v_cndmask_b32_e64 v29, v29, v250, s[40:41]
	s_waitcnt vmcnt(0)
	v_lshlrev_b32_e32 v39, 16, v9
	v_and_b32_e32 v40, 0xffff0000, v8
	v_mov_b32_e32 v32, v16
	v_mov_b32_e32 v33, v16
	v_and_b32_e32 v35, 0xffff0000, v9
	v_lshlrev_b32_e32 v38, 16, v8
	v_mov_b32_e32 v42, v40
	v_mov_b32_e32 v43, v39
	v_mov_b32_e32 v24, v17
	v_mov_b32_e32 v25, v17
	v_mov_b32_e32 v8, v38
	v_mov_b32_e32 v9, v40
	v_pk_mul_f32 v[42:43], v[32:33], v[42:43]
	v_mov_b32_e32 v28, v35
	v_mov_b32_e32 v19, v18
	v_mov_b32_e32 v34, v39
	v_pk_fma_f32 v[8:9], v[24:25], v[8:9], v[42:43]
	v_pk_mul_f32 v[28:29], v[16:17], v[28:29]
	v_mov_b32_e32 v21, v20
	v_lshlrev_b32_e32 v41, 16, v10
	v_pk_fma_f32 v[8:9], v[18:19], v[34:35], v[8:9]
	v_pk_fma_f32 v[28:29], v[16:17], v[38:39], v[28:29] op_sel:[0,0,1] op_sel_hi:[1,1,0]
	v_pk_add_f32 v[8:9], v[20:21], v[8:9]
	v_pk_fma_f32 v[28:29], v[18:19], v[40:41], v[28:29]
	v_and_b32_sdwa v34, v8, v208 dst_sel:DWORD dst_unused:UNUSED_PAD src0_sel:WORD_1 src1_sel:DWORD
	v_pk_add_f32 v[28:29], v[20:21], v[28:29]
	v_and_b32_sdwa v26, v9, v208 dst_sel:DWORD dst_unused:UNUSED_PAD src0_sel:WORD_1 src1_sel:DWORD
	v_add3_u32 v8, v8, v34, s34
	v_and_b32_sdwa v34, v28, v208 dst_sel:DWORD dst_unused:UNUSED_PAD src0_sel:WORD_1 src1_sel:DWORD
	v_lshlrev_b32_e32 v37, 16, v11
	v_add3_u32 v9, v9, v26, s34
	v_and_b32_e32 v8, 0xffff0000, v8
	v_and_b32_sdwa v26, v29, v208 dst_sel:DWORD dst_unused:UNUSED_PAD src0_sel:WORD_1 src1_sel:DWORD
	v_add3_u32 v28, v28, v34, s34
	v_and_b32_e32 v11, 0xffff0000, v11
	v_and_b32_e32 v10, 0xffff0000, v10
	v_add3_u32 v26, v29, v26, s34
	v_or_b32_sdwa v8, v28, v8 dst_sel:DWORD dst_unused:UNUSED_PAD src0_sel:WORD_1 src1_sel:DWORD
	v_pk_mov_b32 v[28:29], v[34:35], v[10:11] op_sel:[1,0]
	v_mov_b32_e32 v34, v41
	v_mov_b32_e32 v35, v37
	v_pk_mul_f32 v[32:33], v[32:33], v[34:35]
	v_mov_b32_e32 v40, v11
	v_pk_fma_f32 v[24:25], v[24:25], v[28:29], v[32:33]
	v_and_b32_e32 v26, 0xffff0000, v26
	v_mov_b32_e32 v36, v10
	v_pk_fma_f32 v[24:25], v[18:19], v[10:11], v[24:25]
	v_pk_mul_f32 v[10:11], v[16:17], v[40:41]
	v_or_b32_sdwa v9, v26, v9 dst_sel:DWORD dst_unused:UNUSED_PAD src0_sel:DWORD src1_sel:WORD_1
	v_pk_fma_f32 v[10:11], v[16:17], v[36:37], v[10:11] op_sel:[0,0,1] op_sel_hi:[1,1,0]
	v_mov_b32_e32 v26, v37
	v_pk_fma_f32 v[10:11], v[18:19], v[26:27], v[10:11]
	v_pk_add_f32 v[24:25], v[20:21], v[24:25]
	v_pk_add_f32 v[10:11], v[20:21], v[10:11]
	v_and_b32_sdwa v16, v25, v208 dst_sel:DWORD dst_unused:UNUSED_PAD src0_sel:WORD_1 src1_sel:DWORD
	v_and_b32_sdwa v18, v11, v208 dst_sel:DWORD dst_unused:UNUSED_PAD src0_sel:WORD_1 src1_sel:DWORD
	v_and_b32_sdwa v19, v10, v208 dst_sel:DWORD dst_unused:UNUSED_PAD src0_sel:WORD_1 src1_sel:DWORD
	v_and_b32_sdwa v17, v24, v208 dst_sel:DWORD dst_unused:UNUSED_PAD src0_sel:WORD_1 src1_sel:DWORD
	v_add3_u32 v11, v11, v18, s34
	v_add3_u32 v10, v10, v19, s34
	v_add3_u32 v17, v24, v17, s34
	v_add3_u32 v16, v25, v16, s34
	v_and_b32_e32 v11, 0xffff0000, v11
	v_and_b32_e32 v10, 0xffff0000, v10
	s_add_i32 s22, s16, 0x200
	v_or_b32_sdwa v11, v11, v16 dst_sel:DWORD dst_unused:UNUSED_PAD src0_sel:DWORD src1_sel:WORD_1
	v_or_b32_sdwa v10, v10, v17 dst_sel:DWORD dst_unused:UNUSED_PAD src0_sel:DWORD src1_sel:WORD_1
	s_ashr_i32 s23, s22, 31
	ds_write_b128 v115, v[8:11] offset:33024
	v_lshl_add_u64 v[10:11], v[14:15], 0, s[22:23]
	v_lshl_add_u64 v[2:3], v[2:3], 1, s[8:9]
	v_lshlrev_b64 v[10:11], 11, v[10:11]
	v_lshlrev_b32_e32 v116, 3, v30
	v_lshl_add_u64 v[88:89], v[2:3], 0, v[10:11]
	v_sub_u32_e32 v10, 0x800, v116
	v_ashrrev_i32_e32 v11, 31, v10
	v_lshlrev_b64 v[92:93], 11, v[10:11]
	v_sub_u32_e32 v10, 0x7ff, v116
	v_ashrrev_i32_e32 v11, 31, v10
	v_lshlrev_b64 v[94:95], 11, v[10:11]
	v_sub_u32_e32 v10, 0x7fe, v116
	v_sub_u32_e32 v8, 0, v30
	v_lshl_add_u64 v[2:3], v[22:23], 0, s[22:23]
	v_ashrrev_i32_e32 v11, 31, v10
	v_ashrrev_i32_e32 v44, 6, v30
	v_and_b32_e32 v16, 7, v8
	v_lshl_add_u64 v[8:9], v[12:13], 1, s[8:9]
	v_lshlrev_b64 v[2:3], 11, v[2:3]
	v_lshlrev_b64 v[96:97], 11, v[10:11]
	v_sub_u32_e32 v10, 0x7fd, v116
	v_and_b32_e32 v45, 15, v30
	v_bfe_u32 v0, v30, 4, 2
	v_lshl_add_u64 v[90:91], v[8:9], 0, v[2:3]
	v_lshlrev_b32_e32 v2, 8, v44
	v_ashrrev_i32_e32 v11, 31, v10
	v_lshlrev_b32_e32 v17, 3, v0
	v_lshl_or_b32 v2, v0, 2, v2
	v_lshlrev_b32_e32 v0, 9, v45
	v_lshlrev_b64 v[98:99], 11, v[10:11]
	v_sub_u32_e32 v10, 0x7fc, v116
	v_lshl_add_u64 v[8:9], v[0:1], 0, s[16:17]
	v_ashrrev_i32_e32 v11, 31, v10
	v_and_b32_e32 v31, 63, v30
	v_mul_u32_u24_e32 v3, 0x408, v45
	v_lshlrev_b64 v[8:9], 11, v[8:9]
	v_lshlrev_b64 v[100:101], 11, v[10:11]
	v_sub_u32_e32 v10, 0x7fb, v116
	v_lshlrev_b32_e32 v119, 1, v2
	s_add_u32 s8, s14, 0x800
	s_movk_i32 s4, 0x100
	v_lshl_add_u64 v[8:9], s[18:19], 0, v[8:9]
	v_ashrrev_i32_e32 v11, 31, v10
	v_lshl_add_u32 v120, v3, 1, v119
	v_ashrrev_i32_e32 v3, 31, v2
	v_lshlrev_b32_e32 v0, 13, v31
	s_addc_u32 s9, s15, 0
	v_cmp_gt_i32_e64 s[44:45], s4, v30
	v_lshlrev_b64 v[102:103], 11, v[10:11]
	v_sub_u32_e32 v10, 0x7fa, v116
	v_lshl_add_u64 v[2:3], v[2:3], 1, v[8:9]
	s_mov_b64 s[18:19], 0xde80000
	v_lshl_add_u64 v[110:111], s[16:17], 2, v[0:1]
	v_and_b32_e32 v0, 48, v30
	s_movk_i32 s4, 0x1020
	s_add_u32 s12, s14, 0x2000
	v_ashrrev_i32_e32 v11, 31, v10
	v_lshl_add_u64 v[108:109], v[2:3], 0, s[18:19]
	v_mad_u32_u24 v122, v45, s25, v0
	v_mad_u32_u24 v0, v16, s4, v0
	v_add_lshl_u32 v2, v16, v45, 1
	s_addc_u32 s13, s15, 0
	v_readlane_b32 s22, v253, 55
	v_lshlrev_b64 v[104:105], 11, v[10:11]
	v_sub_u32_e32 v10, 0x7f9, v116
	v_sub_u32_e32 v0, v0, v2
	v_lshlrev_b32_e32 v2, 9, v44
	s_add_u32 s14, s14, 0x3800
	v_readlane_b32 s23, v253, 56
	v_ashrrev_i32_e32 v11, 31, v10
	v_sub_u32_e32 v0, v0, v2
	s_mov_b32 s20, 0
	s_addc_u32 s15, s15, 0
	v_lshlrev_b32_e32 v117, 4, v30
	v_cmp_gt_i32_e64 s[46:47], 2, v30
	s_add_i32 s27, s16, s22
	v_cmp_lt_u32_e64 s[48:49], 3, v45
	v_cmp_gt_u32_e64 s[50:51], 4, v45
	v_mul_u32_u24_e32 v118, 0x810, v45
	v_cmp_lt_i32_e64 s[52:53], 0, v30
	v_cmp_lt_i32_e64 s[54:55], -1, v30
	v_lshlrev_b64 v[106:107], 11, v[10:11]
	v_or_b32_e32 v121, 0xffffffc0, v31
	v_add_u32_e32 v123, 0x620, v0
	s_mov_b64 s[18:19], -1
	s_mov_b64 s[22:23], 0
	v_lshlrev_b32_e32 v124, 1, v17
	s_branch .LBB0_1633

.LBB0_1633:
	s_andn2_b64 vcc, exec, s[22:23]
	s_cbranch_vccnz .LBB0_1643
	global_load_dword v15, v1, s[8:9]
	global_load_dword v14, v1, s[12:13]
	global_load_dword v12, v1, s[14:15]
	global_load_dword v2, v1, s[2:3] offset:2048
	global_load_dwordx4 v[8:11], v[88:89], off
	v_mov_b32_e32 v17, 0
	v_mov_b32_e32 v19, 0
	s_and_saveexec_b64 s[16:17], s[36:37]
	s_cbranch_execz .LBB0_1636
	global_load_ushort v251, v[88:89], off offset:-2

.LBB0_1638:
	s_or_b64 exec, exec, s[16:17]
	s_waitcnt vmcnt(0)
	v_lshlrev_b32_e32 v250, 16, v251
	v_cndmask_b32_e64 v19, v19, v250, s[36:37]
	s_waitcnt vmcnt(0)
	v_lshlrev_b32_e32 v25, 16, v9
	v_and_b32_e32 v26, 0xffff0000, v8
	v_and_b32_e32 v21, 0xffff0000, v9
	v_lshlrev_b32_e32 v24, 16, v8
	v_mov_b32_e32 v28, v26
	v_mov_b32_e32 v29, v25
	v_mov_b32_e32 v8, v24
	v_mov_b32_e32 v9, v26
	v_mov_b32_e32 v0, v15
	v_pk_mul_f32 v[28:29], v[14:15], v[28:29] op_sel_hi:[0,1]
	v_mov_b32_e32 v18, v21
	v_mov_b32_e32 v20, v25
	v_pk_fma_f32 v[8:9], v[0:1], v[8:9], v[28:29] op_sel_hi:[0,1,1]
	v_pk_mul_f32 v[18:19], v[14:15], v[18:19]
	v_lshlrev_b32_e32 v27, 16, v10
	v_pk_fma_f32 v[8:9], v[12:13], v[20:21], v[8:9] op_sel_hi:[0,1,1]
	v_pk_fma_f32 v[18:19], v[14:15], v[24:25], v[18:19] op_sel:[0,0,1] op_sel_hi:[1,1,0]
	v_pk_add_f32 v[8:9], v[2:3], v[8:9] op_sel_hi:[0,1]
	v_pk_fma_f32 v[18:19], v[12:13], v[26:27], v[18:19] op_sel_hi:[0,1,1]
	v_pk_add_f32 v[18:19], v[2:3], v[18:19] op_sel_hi:[0,1]
	v_and_b32_sdwa v3, v9, v208 dst_sel:DWORD dst_unused:UNUSED_PAD src0_sel:WORD_1 src1_sel:DWORD
	v_and_b32_sdwa v13, v8, v208 dst_sel:DWORD dst_unused:UNUSED_PAD src0_sel:WORD_1 src1_sel:DWORD
	v_lshlrev_b32_e32 v23, 16, v11
	v_add3_u32 v3, v9, v3, s34
	v_add3_u32 v8, v8, v13, s34
	v_and_b32_sdwa v9, v19, v208 dst_sel:DWORD dst_unused:UNUSED_PAD src0_sel:WORD_1 src1_sel:DWORD
	v_and_b32_sdwa v13, v18, v208 dst_sel:DWORD dst_unused:UNUSED_PAD src0_sel:WORD_1 src1_sel:DWORD
	v_and_b32_e32 v11, 0xffff0000, v11
	v_and_b32_e32 v10, 0xffff0000, v10
	v_add3_u32 v9, v19, v9, s34
	v_add3_u32 v13, v18, v13, s34
	v_pk_mov_b32 v[18:19], v[20:21], v[10:11] op_sel:[1,0]
	v_mov_b32_e32 v20, v27
	v_mov_b32_e32 v21, v23
	v_pk_mul_f32 v[20:21], v[14:15], v[20:21] op_sel_hi:[0,1]
	v_pk_fma_f32 v[18:19], v[0:1], v[18:19], v[20:21] op_sel_hi:[0,1,1]
	v_mov_b32_e32 v26, v11
	v_mov_b32_e32 v22, v10
	v_pk_fma_f32 v[18:19], v[12:13], v[10:11], v[18:19] op_sel_hi:[0,1,1]
	v_pk_mul_f32 v[10:11], v[14:15], v[26:27]
	v_mov_b32_e32 v16, v23
	v_pk_fma_f32 v[10:11], v[14:15], v[22:23], v[10:11] op_sel:[0,0,1] op_sel_hi:[1,1,0]
	v_and_b32_e32 v8, 0xffff0000, v8
	v_pk_fma_f32 v[10:11], v[12:13], v[16:17], v[10:11] op_sel_hi:[0,1,1]
	v_pk_add_f32 v[10:11], v[2:3], v[10:11] op_sel_hi:[0,1]
	v_and_b32_e32 v9, 0xffff0000, v9
	v_or_b32_sdwa v8, v13, v8 dst_sel:DWORD dst_unused:UNUSED_PAD src0_sel:WORD_1 src1_sel:DWORD
	v_pk_add_f32 v[18:19], v[2:3], v[18:19] op_sel_hi:[0,1]
	v_and_b32_sdwa v13, v11, v208 dst_sel:DWORD dst_unused:UNUSED_PAD src0_sel:WORD_1 src1_sel:DWORD
	v_and_b32_sdwa v16, v10, v208 dst_sel:DWORD dst_unused:UNUSED_PAD src0_sel:WORD_1 src1_sel:DWORD
	v_or_b32_sdwa v9, v9, v3 dst_sel:DWORD dst_unused:UNUSED_PAD src0_sel:DWORD src1_sel:WORD_1
	v_and_b32_sdwa v0, v19, v208 dst_sel:DWORD dst_unused:UNUSED_PAD src0_sel:WORD_1 src1_sel:DWORD
	v_and_b32_sdwa v3, v18, v208 dst_sel:DWORD dst_unused:UNUSED_PAD src0_sel:WORD_1 src1_sel:DWORD
	v_add3_u32 v11, v11, v13, s34
	v_add3_u32 v10, v10, v16, s34
	v_add3_u32 v3, v18, v3, s34
	v_add3_u32 v0, v19, v0, s34
	v_and_b32_e32 v11, 0xffff0000, v11
	v_and_b32_e32 v10, 0xffff0000, v10
	v_or_b32_sdwa v11, v11, v0 dst_sel:DWORD dst_unused:UNUSED_PAD src0_sel:DWORD src1_sel:WORD_1
	v_or_b32_sdwa v10, v10, v3 dst_sel:DWORD dst_unused:UNUSED_PAD src0_sel:DWORD src1_sel:WORD_1
	ds_write_b128 v114, v[8:11] offset:41280
	global_load_dwordx4 v[8:11], v[90:91], off
	v_mov_b32_e32 v17, 0
	v_mov_b32_e32 v19, 0
	s_and_saveexec_b64 s[16:17], s[40:41]
	s_cbranch_execz .LBB0_1640
	global_load_ushort v251, v[90:91], off offset:-2

.LBB0_1642:
	s_or_b64 exec, exec, s[16:17]
	s_waitcnt vmcnt(0)
	v_lshlrev_b32_e32 v250, 16, v251
	v_cndmask_b32_e64 v19, v19, v250, s[40:41]
	s_waitcnt vmcnt(0)
	v_lshlrev_b32_e32 v29, 16, v9
	v_and_b32_e32 v30, 0xffff0000, v8
	v_mov_b32_e32 v22, v14
	v_mov_b32_e32 v23, v14
	v_and_b32_e32 v25, 0xffff0000, v9
	v_lshlrev_b32_e32 v28, 16, v8
	v_mov_b32_e32 v32, v30
	v_mov_b32_e32 v33, v29
	v_mov_b32_e32 v20, v15
	v_mov_b32_e32 v21, v15
	v_mov_b32_e32 v8, v28
	v_mov_b32_e32 v9, v30
	v_pk_mul_f32 v[32:33], v[22:23], v[32:33]
	v_mov_b32_e32 v18, v25
	v_mov_b32_e32 v13, v12
	v_mov_b32_e32 v24, v29
	v_pk_fma_f32 v[8:9], v[20:21], v[8:9], v[32:33]
	v_pk_mul_f32 v[18:19], v[14:15], v[18:19]
	v_mov_b32_e32 v3, v2
	v_lshlrev_b32_e32 v31, 16, v10
	v_pk_fma_f32 v[8:9], v[12:13], v[24:25], v[8:9]
	v_pk_fma_f32 v[18:19], v[14:15], v[28:29], v[18:19] op_sel:[0,0,1] op_sel_hi:[1,1,0]
	v_pk_add_f32 v[8:9], v[2:3], v[8:9]
	v_pk_fma_f32 v[18:19], v[12:13], v[30:31], v[18:19]
	v_and_b32_sdwa v0, v9, v208 dst_sel:DWORD dst_unused:UNUSED_PAD src0_sel:WORD_1 src1_sel:DWORD
	v_pk_add_f32 v[18:19], v[2:3], v[18:19]
	v_and_b32_sdwa v16, v8, v208 dst_sel:DWORD dst_unused:UNUSED_PAD src0_sel:WORD_1 src1_sel:DWORD
	v_lshlrev_b32_e32 v27, 16, v11
	v_add3_u32 v0, v9, v0, s34
	v_add3_u32 v8, v8, v16, s34
	v_and_b32_sdwa v9, v19, v208 dst_sel:DWORD dst_unused:UNUSED_PAD src0_sel:WORD_1 src1_sel:DWORD
	v_and_b32_sdwa v16, v18, v208 dst_sel:DWORD dst_unused:UNUSED_PAD src0_sel:WORD_1 src1_sel:DWORD
	v_and_b32_e32 v11, 0xffff0000, v11
	v_and_b32_e32 v10, 0xffff0000, v10
	v_add3_u32 v9, v19, v9, s34
	v_add3_u32 v16, v18, v16, s34
	v_pk_mov_b32 v[18:19], v[24:25], v[10:11] op_sel:[1,0]
	v_mov_b32_e32 v24, v31
	v_mov_b32_e32 v25, v27
	v_pk_mul_f32 v[22:23], v[22:23], v[24:25]
	v_mov_b32_e32 v30, v11
	v_pk_fma_f32 v[18:19], v[20:21], v[18:19], v[22:23]
	v_and_b32_e32 v8, 0xffff0000, v8
	v_mov_b32_e32 v26, v10
	v_pk_fma_f32 v[18:19], v[12:13], v[10:11], v[18:19]
	v_pk_mul_f32 v[10:11], v[14:15], v[30:31]
	v_or_b32_sdwa v8, v16, v8 dst_sel:DWORD dst_unused:UNUSED_PAD src0_sel:WORD_1 src1_sel:DWORD
	v_pk_fma_f32 v[10:11], v[14:15], v[26:27], v[10:11] op_sel:[0,0,1] op_sel_hi:[1,1,0]
	v_mov_b32_e32 v16, v27
	v_pk_fma_f32 v[10:11], v[12:13], v[16:17], v[10:11]
	v_pk_add_f32 v[18:19], v[2:3], v[18:19]
	v_pk_add_f32 v[2:3], v[2:3], v[10:11]
	v_and_b32_e32 v9, 0xffff0000, v9
	v_and_b32_sdwa v11, v3, v208 dst_sel:DWORD dst_unused:UNUSED_PAD src0_sel:WORD_1 src1_sel:DWORD
	v_and_b32_sdwa v12, v2, v208 dst_sel:DWORD dst_unused:UNUSED_PAD src0_sel:WORD_1 src1_sel:DWORD
	v_or_b32_sdwa v9, v9, v0 dst_sel:DWORD dst_unused:UNUSED_PAD src0_sel:DWORD src1_sel:WORD_1
	v_and_b32_sdwa v0, v19, v208 dst_sel:DWORD dst_unused:UNUSED_PAD src0_sel:WORD_1 src1_sel:DWORD
	v_and_b32_sdwa v10, v18, v208 dst_sel:DWORD dst_unused:UNUSED_PAD src0_sel:WORD_1 src1_sel:DWORD
	v_add3_u32 v3, v3, v11, s34
	v_add3_u32 v2, v2, v12, s34
	v_add3_u32 v10, v18, v10, s34
	v_add3_u32 v0, v19, v0, s34
	v_and_b32_e32 v3, 0xffff0000, v3
	v_and_b32_e32 v2, 0xffff0000, v2
	v_or_b32_sdwa v11, v3, v0 dst_sel:DWORD dst_unused:UNUSED_PAD src0_sel:DWORD src1_sel:WORD_1
	v_or_b32_sdwa v10, v2, v10 dst_sel:DWORD dst_unused:UNUSED_PAD src0_sel:DWORD src1_sel:WORD_1
	ds_write_b128 v115, v[8:11] offset:41280

.LBB0_1808:
	s_or_b64 exec, exec, s[0:1]
	s_waitcnt lgkmcnt(0)
	s_barrier
	ds_read_b32 v0, v1 offset:58392
	s_movk_i32 s0, 0x3ff
	s_waitcnt lgkmcnt(0)
	v_cmp_lt_i32_e32 vcc, s0, v0
	v_readfirstlane_b32 s4, v0
	s_mov_b64 s[0:1], -1
	s_cbranch_vccnz .LBB0_1803
	v_mov_b32_e32 v30, v196
	s_ashr_i32 s8, s4, 1
	s_mov_b64 s[0:1], s[62:63]
	v_readlane_b32 s36, v253, 34
	s_add_u32 s14, s0, 0x7680000
	v_readlane_b32 s48, v253, 46
	v_readlane_b32 s49, v253, 47
	s_addc_u32 s15, s1, 0
	s_mov_b64 s[12:13], s[62:63]
	s_mov_b64 s[0:1], s[48:49]
	v_readlane_b32 s2, v255, 14
	s_add_u32 s16, s0, s2
	v_readlane_b32 s2, v255, 15
	v_readlane_b32 s50, v253, 48
	v_readlane_b32 s51, v253, 49
	v_readlane_b32 s3, v255, 16
	s_addc_u32 s17, s1, 0
	s_mov_b64 s[0:1], s[50:51]
	s_lshl_b64 s[2:3], s[2:3], 2
	s_add_u32 s2, s0, s2
	s_addc_u32 s3, s1, s3
	s_ashr_i32 s9, s8, 31
	s_lshl_b64 s[0:1], s[8:9], 2
	s_add_u32 s16, s16, s0
	s_addc_u32 s17, s17, s1
	v_mov_b32_e32 v0, 0x3000
	s_barrier
	global_load_dword v18, v207, s[16:17] offset:2048
	global_load_dword v16, v0, s[16:17]
	v_ashrrev_i32_e32 v0, 31, v30
	s_add_u32 s2, s2, s0
	v_lshrrev_b32_e32 v0, 27, v0
	s_addc_u32 s3, s3, s1
	v_add_u32_e32 v2, v30, v0
	s_lshl_b32 s4, s4, 4
	v_ashrrev_i32_e32 v0, 5, v2
	s_and_b32 s4, s4, 16
	v_and_b32_e32 v2, 0xffffffe0, v2
	v_add_u32_e32 v17, s4, v0
	v_mov_b64_e32 v[8:9], s[8:9]
	s_movk_i32 s24, 0x600
	v_sub_u32_e32 v12, v30, v2
	v_mad_i64_i32 v[8:9], s[18:19], v17, s24, v[8:9]
	v_lshlrev_b32_e32 v2, 3, v12
	v_lshlrev_b64 v[8:9], 9, v[8:9]
	v_lshl_add_u64 v[8:9], s[14:15], 0, v[8:9]
	v_ashrrev_i32_e32 v3, 31, v2
	v_lshl_add_u64 v[22:23], v[2:3], 1, v[8:9]
	global_load_dword v19, v1, s[16:17]
	global_load_dword v20, v1, s[2:3]
	global_load_dwordx4 v[8:11], v[22:23], off
	v_readlane_b32 s37, v253, 35
	v_cmp_lt_i32_e64 s[36:37], 0, v12
	v_mov_b32_e32 v13, 0
	v_mov_b32_e32 v15, 0
	v_readlane_b32 s38, v253, 36
	v_readlane_b32 s39, v253, 37
	v_readlane_b32 s40, v253, 38
	v_readlane_b32 s41, v253, 39
	v_readlane_b32 s42, v253, 40
	v_readlane_b32 s43, v253, 41
	v_readlane_b32 s44, v253, 42
	v_readlane_b32 s45, v253, 43
	v_readlane_b32 s46, v253, 44
	v_readlane_b32 s47, v253, 45
	s_and_saveexec_b64 s[18:19], s[36:37]
	s_cbranch_execz .LBB0_1811
	global_load_ushort v251, v[22:23], off offset:-2

.LBB0_1813:
	s_or_b64 exec, exec, s[18:19]
	s_waitcnt vmcnt(0)
	v_lshlrev_b32_e32 v250, 16, v251
	v_cndmask_b32_e64 v15, v15, v250, s[36:37]
	s_waitcnt vmcnt(0)
	v_lshlrev_b32_e32 v27, 16, v9
	v_and_b32_e32 v28, 0xffff0000, v8
	v_and_b32_e32 v23, 0xffff0000, v9
	v_lshlrev_b32_e32 v26, 16, v8
	v_mov_b32_e32 v32, v28
	v_mov_b32_e32 v33, v27
	v_mov_b32_e32 v8, v26
	v_mov_b32_e32 v9, v28
	v_mov_b32_e32 v12, v19
	v_pk_mul_f32 v[32:33], v[18:19], v[32:33] op_sel_hi:[0,1]
	v_mov_b32_e32 v14, v23
	v_mov_b32_e32 v22, v27
	v_pk_fma_f32 v[8:9], v[12:13], v[8:9], v[32:33] op_sel_hi:[0,1,1]
	v_pk_mul_f32 v[14:15], v[18:19], v[14:15]
	v_lshlrev_b32_e32 v29, 16, v10
	v_pk_fma_f32 v[8:9], v[16:17], v[22:23], v[8:9] op_sel_hi:[0,1,1]
	v_pk_fma_f32 v[14:15], v[18:19], v[26:27], v[14:15] op_sel:[0,0,1] op_sel_hi:[1,1,0]
	v_pk_add_f32 v[8:9], v[20:21], v[8:9] op_sel_hi:[0,1]
	v_pk_fma_f32 v[14:15], v[16:17], v[28:29], v[14:15] op_sel_hi:[0,1,1]
	v_pk_add_f32 v[14:15], v[20:21], v[14:15] op_sel_hi:[0,1]
	v_and_b32_sdwa v21, v9, v208 dst_sel:DWORD dst_unused:UNUSED_PAD src0_sel:WORD_1 src1_sel:DWORD
	v_and_b32_sdwa v22, v8, v208 dst_sel:DWORD dst_unused:UNUSED_PAD src0_sel:WORD_1 src1_sel:DWORD
	v_add3_u32 v9, v9, v21, s34
	v_and_b32_sdwa v21, v15, v208 dst_sel:DWORD dst_unused:UNUSED_PAD src0_sel:WORD_1 src1_sel:DWORD
	v_add3_u32 v8, v8, v22, s34
	v_and_b32_sdwa v22, v14, v208 dst_sel:DWORD dst_unused:UNUSED_PAD src0_sel:WORD_1 src1_sel:DWORD
	v_add3_u32 v15, v15, v21, s34
	v_lshlrev_b32_e32 v25, 16, v11
	v_and_b32_e32 v8, 0xffff0000, v8
	v_add3_u32 v14, v14, v22, s34
	v_and_b32_e32 v15, 0xffff0000, v15
	v_and_b32_e32 v11, 0xffff0000, v11
	v_and_b32_e32 v10, 0xffff0000, v10
	v_or_b32_sdwa v9, v15, v9 dst_sel:DWORD dst_unused:UNUSED_PAD src0_sel:DWORD src1_sel:WORD_1
	v_or_b32_sdwa v8, v14, v8 dst_sel:DWORD dst_unused:UNUSED_PAD src0_sel:WORD_1 src1_sel:DWORD
	v_pk_mov_b32 v[14:15], v[22:23], v[10:11] op_sel:[1,0]
	v_mov_b32_e32 v22, v29
	v_mov_b32_e32 v23, v25
	v_pk_mul_f32 v[22:23], v[18:19], v[22:23] op_sel_hi:[0,1]
	v_pk_fma_f32 v[14:15], v[12:13], v[14:15], v[22:23] op_sel_hi:[0,1,1]
	v_mov_b32_e32 v28, v11
	v_mov_b32_e32 v24, v10
	v_pk_fma_f32 v[14:15], v[16:17], v[10:11], v[14:15] op_sel_hi:[0,1,1]
	v_pk_mul_f32 v[10:11], v[18:19], v[28:29]
	v_mov_b32_e32 v12, v25
	v_pk_fma_f32 v[10:11], v[18:19], v[24:25], v[10:11] op_sel:[0,0,1] op_sel_hi:[1,1,0]
	v_pk_add_f32 v[14:15], v[20:21], v[14:15] op_sel_hi:[0,1]
	v_pk_fma_f32 v[10:11], v[16:17], v[12:13], v[10:11] op_sel_hi:[0,1,1]
	v_pk_add_f32 v[10:11], v[20:21], v[10:11] op_sel_hi:[0,1]
	v_and_b32_sdwa v12, v15, v208 dst_sel:DWORD dst_unused:UNUSED_PAD src0_sel:WORD_1 src1_sel:DWORD
	v_and_b32_sdwa v13, v14, v208 dst_sel:DWORD dst_unused:UNUSED_PAD src0_sel:WORD_1 src1_sel:DWORD
	v_add3_u32 v13, v14, v13, s34
	v_add3_u32 v12, v15, v12, s34
	v_and_b32_sdwa v14, v11, v208 dst_sel:DWORD dst_unused:UNUSED_PAD src0_sel:WORD_1 src1_sel:DWORD
	v_and_b32_sdwa v15, v10, v208 dst_sel:DWORD dst_unused:UNUSED_PAD src0_sel:WORD_1 src1_sel:DWORD
	v_add3_u32 v11, v11, v14, s34
	v_add3_u32 v10, v10, v15, s34
	s_movk_i32 s18, 0x210
	v_and_b32_e32 v11, 0xffff0000, v11
	v_and_b32_e32 v10, 0xffff0000, v10
	v_mul_lo_u32 v0, v0, s18
	v_or_b32_sdwa v11, v11, v12 dst_sel:DWORD dst_unused:UNUSED_PAD src0_sel:DWORD src1_sel:WORD_1
	v_or_b32_sdwa v10, v10, v13 dst_sel:DWORD dst_unused:UNUSED_PAD src0_sel:DWORD src1_sel:WORD_1
	v_lshl_add_u32 v64, v2, 1, v0
	v_add_u32_e32 v0, 0x100, v30
	ds_write_b128 v64, v[8:11] offset:16896
	v_ashrrev_i32_e32 v8, 31, v0
	v_lshrrev_b32_e32 v8, 27, v8
	v_add_u32_e32 v8, v0, v8
	v_ashrrev_i32_e32 v26, 5, v8
	v_and_b32_e32 v8, 0xffffffe0, v8
	v_sub_u32_e32 v21, v0, v8
	v_add_u32_e32 v0, s4, v26
	v_mov_b64_e32 v[8:9], s[8:9]
	v_mad_i64_i32 v[8:9], s[18:19], v0, s24, v[8:9]
	v_lshlrev_b32_e32 v12, 3, v21
	v_lshlrev_b64 v[8:9], 9, v[8:9]
	v_lshl_add_u64 v[8:9], s[14:15], 0, v[8:9]
	v_ashrrev_i32_e32 v13, 31, v12
	v_lshl_add_u64 v[14:15], v[12:13], 1, v[8:9]
	global_load_dwordx4 v[8:11], v[14:15], off
	v_cmp_lt_i32_e64 s[40:41], 0, v21
	v_mov_b32_e32 v23, 0
	v_mov_b32_e32 v25, 0
	s_and_saveexec_b64 s[18:19], s[40:41]
	s_cbranch_execz .LBB0_1815
	global_load_ushort v251, v[14:15], off offset:-2

.LBB0_1817:
	s_or_b64 exec, exec, s[18:19]
	s_waitcnt vmcnt(0)
	v_lshlrev_b32_e32 v250, 16, v251
	v_cndmask_b32_e64 v25, v25, v250, s[40:41]
	s_waitcnt vmcnt(0)
	v_lshlrev_b32_e32 v39, 16, v9
	v_and_b32_e32 v40, 0xffff0000, v8
	v_mov_b32_e32 v32, v18
	v_mov_b32_e32 v33, v18
	v_and_b32_e32 v35, 0xffff0000, v9
	v_lshlrev_b32_e32 v38, 16, v8
	v_mov_b32_e32 v42, v40
	v_mov_b32_e32 v43, v39
	v_mov_b32_e32 v28, v19
	v_mov_b32_e32 v29, v19
	v_mov_b32_e32 v8, v38
	v_mov_b32_e32 v9, v40
	v_pk_mul_f32 v[42:43], v[32:33], v[42:43]
	v_mov_b32_e32 v24, v35
	v_mad_i64_i32 v[14:15], s[18:19], v17, s24, 0
	v_mov_b32_e32 v17, v16
	v_mov_b32_e32 v34, v39
	v_pk_fma_f32 v[8:9], v[28:29], v[8:9], v[42:43]
	v_pk_mul_f32 v[24:25], v[18:19], v[24:25]
	v_mov_b32_e32 v21, v20
	v_lshlrev_b32_e32 v41, 16, v10
	v_pk_fma_f32 v[8:9], v[16:17], v[34:35], v[8:9]
	v_pk_fma_f32 v[24:25], v[18:19], v[38:39], v[24:25] op_sel:[0,0,1] op_sel_hi:[1,1,0]
	v_pk_add_f32 v[8:9], v[20:21], v[8:9]
	v_pk_fma_f32 v[24:25], v[16:17], v[40:41], v[24:25]
	v_and_b32_sdwa v27, v8, v208 dst_sel:DWORD dst_unused:UNUSED_PAD src0_sel:WORD_1 src1_sel:DWORD
	v_pk_add_f32 v[24:25], v[20:21], v[24:25]
	v_and_b32_sdwa v22, v9, v208 dst_sel:DWORD dst_unused:UNUSED_PAD src0_sel:WORD_1 src1_sel:DWORD
	v_add3_u32 v8, v8, v27, s34
	v_and_b32_sdwa v27, v24, v208 dst_sel:DWORD dst_unused:UNUSED_PAD src0_sel:WORD_1 src1_sel:DWORD
	v_lshlrev_b32_e32 v37, 16, v11
	v_add3_u32 v9, v9, v22, s34
	v_and_b32_e32 v8, 0xffff0000, v8
	v_and_b32_sdwa v22, v25, v208 dst_sel:DWORD dst_unused:UNUSED_PAD src0_sel:WORD_1 src1_sel:DWORD
	v_add3_u32 v24, v24, v27, s34
	v_and_b32_e32 v11, 0xffff0000, v11
	v_and_b32_e32 v10, 0xffff0000, v10
	v_add3_u32 v22, v25, v22, s34
	v_or_b32_sdwa v8, v24, v8 dst_sel:DWORD dst_unused:UNUSED_PAD src0_sel:WORD_1 src1_sel:DWORD
	v_pk_mov_b32 v[24:25], v[34:35], v[10:11] op_sel:[1,0]
	v_mov_b32_e32 v34, v41
	v_mov_b32_e32 v35, v37
	v_pk_mul_f32 v[32:33], v[32:33], v[34:35]
	v_mov_b32_e32 v40, v11
	v_pk_fma_f32 v[24:25], v[28:29], v[24:25], v[32:33]
	v_and_b32_e32 v22, 0xffff0000, v22
	v_mov_b32_e32 v36, v10
	v_pk_fma_f32 v[24:25], v[16:17], v[10:11], v[24:25]
	v_pk_mul_f32 v[10:11], v[18:19], v[40:41]
	v_or_b32_sdwa v9, v22, v9 dst_sel:DWORD dst_unused:UNUSED_PAD src0_sel:DWORD src1_sel:WORD_1
	v_pk_fma_f32 v[10:11], v[18:19], v[36:37], v[10:11] op_sel:[0,0,1] op_sel_hi:[1,1,0]
	v_mov_b32_e32 v22, v37
	v_pk_fma_f32 v[10:11], v[16:17], v[22:23], v[10:11]
	v_pk_add_f32 v[24:25], v[20:21], v[24:25]
	v_pk_add_f32 v[10:11], v[20:21], v[10:11]
	v_and_b32_sdwa v16, v25, v208 dst_sel:DWORD dst_unused:UNUSED_PAD src0_sel:WORD_1 src1_sel:DWORD
	v_and_b32_sdwa v18, v11, v208 dst_sel:DWORD dst_unused:UNUSED_PAD src0_sel:WORD_1 src1_sel:DWORD
	v_and_b32_sdwa v19, v10, v208 dst_sel:DWORD dst_unused:UNUSED_PAD src0_sel:WORD_1 src1_sel:DWORD
	v_add3_u32 v11, v11, v18, s34
	v_and_b32_sdwa v17, v24, v208 dst_sel:DWORD dst_unused:UNUSED_PAD src0_sel:WORD_1 src1_sel:DWORD
	v_add3_u32 v16, v25, v16, s34
	v_add3_u32 v10, v10, v19, s34
	v_and_b32_e32 v11, 0xffff0000, v11
	s_movk_i32 s18, 0x210
	v_add3_u32 v17, v24, v17, s34
	v_and_b32_e32 v10, 0xffff0000, v10
	v_or_b32_sdwa v11, v11, v16 dst_sel:DWORD dst_unused:UNUSED_PAD src0_sel:DWORD src1_sel:WORD_1
	v_mul_lo_u32 v16, v26, s18
	v_or_b32_sdwa v10, v10, v17 dst_sel:DWORD dst_unused:UNUSED_PAD src0_sel:DWORD src1_sel:WORD_1
	v_lshl_add_u32 v65, v12, 1, v16
	ds_write_b128 v65, v[8:11] offset:16896
	s_add_i32 s18, s8, 0x400
	v_mov_b32_e32 v8, 0x2000
	s_ashr_i32 s19, s18, 31
	global_load_dword v17, v207, s[16:17]
	global_load_dword v16, v8, s[16:17] offset:2048
	v_mov_b32_e32 v8, 0x4000
	global_load_dword v18, v8, s[16:17]
	global_load_dword v20, v207, s[2:3]
	v_lshl_add_u64 v[8:9], v[14:15], 0, s[18:19]
	v_lshlrev_b64 v[8:9], 9, v[8:9]
	v_lshl_add_u64 v[8:9], s[14:15], 0, v[8:9]
	v_lshl_add_u64 v[22:23], v[2:3], 1, v[8:9]
	global_load_dwordx4 v[8:11], v[22:23], off
	v_mov_b32_e32 v25, 0
	v_mov_b32_e32 v27, 0
	s_and_saveexec_b64 s[20:21], s[36:37]
	s_cbranch_execz .LBB0_1819
	global_load_ushort v251, v[22:23], off offset:-2

.LBB0_1821:
	s_or_b64 exec, exec, s[20:21]
	s_waitcnt vmcnt(0)
	v_lshlrev_b32_e32 v250, 16, v251
	v_cndmask_b32_e64 v27, v27, v250, s[36:37]
	s_waitcnt vmcnt(0)
	v_lshlrev_b32_e32 v35, 16, v9
	v_and_b32_e32 v36, 0xffff0000, v8
	v_and_b32_e32 v29, 0xffff0000, v9
	v_lshlrev_b32_e32 v34, 16, v8
	v_mov_b32_e32 v38, v36
	v_mov_b32_e32 v39, v35
	v_mad_i64_i32 v[22:23], s[20:21], v0, s24, 0
	v_mov_b32_e32 v8, v34
	v_mov_b32_e32 v9, v36
	v_mov_b32_e32 v0, v17
	v_pk_mul_f32 v[38:39], v[16:17], v[38:39] op_sel_hi:[0,1]
	v_mov_b32_e32 v26, v29
	v_mov_b32_e32 v28, v35
	v_pk_fma_f32 v[8:9], v[0:1], v[8:9], v[38:39] op_sel_hi:[0,1,1]
	v_pk_mul_f32 v[26:27], v[16:17], v[26:27]
	v_lshlrev_b32_e32 v37, 16, v10
	v_pk_fma_f32 v[8:9], v[18:19], v[28:29], v[8:9] op_sel_hi:[0,1,1]
	v_pk_fma_f32 v[26:27], v[16:17], v[34:35], v[26:27] op_sel:[0,0,1] op_sel_hi:[1,1,0]
	v_pk_add_f32 v[8:9], v[20:21], v[8:9] op_sel_hi:[0,1]
	v_pk_fma_f32 v[26:27], v[18:19], v[36:37], v[26:27] op_sel_hi:[0,1,1]
	v_pk_add_f32 v[26:27], v[20:21], v[26:27] op_sel_hi:[0,1]
	v_and_b32_sdwa v19, v9, v208 dst_sel:DWORD dst_unused:UNUSED_PAD src0_sel:WORD_1 src1_sel:DWORD
	v_and_b32_sdwa v21, v8, v208 dst_sel:DWORD dst_unused:UNUSED_PAD src0_sel:WORD_1 src1_sel:DWORD
	v_lshlrev_b32_e32 v33, 16, v11
	v_add3_u32 v9, v9, v19, s34
	v_add3_u32 v8, v8, v21, s34
	v_and_b32_sdwa v19, v27, v208 dst_sel:DWORD dst_unused:UNUSED_PAD src0_sel:WORD_1 src1_sel:DWORD
	v_and_b32_sdwa v21, v26, v208 dst_sel:DWORD dst_unused:UNUSED_PAD src0_sel:WORD_1 src1_sel:DWORD
	v_and_b32_e32 v11, 0xffff0000, v11
	v_and_b32_e32 v10, 0xffff0000, v10
	v_add3_u32 v19, v27, v19, s34
	v_add3_u32 v21, v26, v21, s34
	v_pk_mov_b32 v[26:27], v[28:29], v[10:11] op_sel:[1,0]
	v_mov_b32_e32 v28, v37
	v_mov_b32_e32 v29, v33
	v_pk_mul_f32 v[28:29], v[16:17], v[28:29] op_sel_hi:[0,1]
	v_and_b32_e32 v19, 0xffff0000, v19
	v_pk_fma_f32 v[26:27], v[0:1], v[26:27], v[28:29] op_sel_hi:[0,1,1]
	v_mov_b32_e32 v36, v11
	v_mov_b32_e32 v32, v10
	v_pk_fma_f32 v[26:27], v[18:19], v[10:11], v[26:27] op_sel_hi:[0,1,1]
	v_pk_mul_f32 v[10:11], v[16:17], v[36:37]
	v_mov_b32_e32 v24, v33
	v_pk_fma_f32 v[10:11], v[16:17], v[32:33], v[10:11] op_sel:[0,0,1] op_sel_hi:[1,1,0]
	v_and_b32_e32 v8, 0xffff0000, v8
	v_pk_fma_f32 v[10:11], v[18:19], v[24:25], v[10:11] op_sel_hi:[0,1,1]
	v_pk_add_f32 v[10:11], v[20:21], v[10:11] op_sel_hi:[0,1]
	v_or_b32_sdwa v8, v21, v8 dst_sel:DWORD dst_unused:UNUSED_PAD src0_sel:WORD_1 src1_sel:DWORD
	v_pk_add_f32 v[26:27], v[20:21], v[26:27] op_sel_hi:[0,1]
	v_and_b32_sdwa v21, v11, v208 dst_sel:DWORD dst_unused:UNUSED_PAD src0_sel:WORD_1 src1_sel:DWORD
	v_and_b32_sdwa v24, v10, v208 dst_sel:DWORD dst_unused:UNUSED_PAD src0_sel:WORD_1 src1_sel:DWORD
	v_or_b32_sdwa v9, v19, v9 dst_sel:DWORD dst_unused:UNUSED_PAD src0_sel:DWORD src1_sel:WORD_1
	v_and_b32_sdwa v0, v27, v208 dst_sel:DWORD dst_unused:UNUSED_PAD src0_sel:WORD_1 src1_sel:DWORD
	v_and_b32_sdwa v19, v26, v208 dst_sel:DWORD dst_unused:UNUSED_PAD src0_sel:WORD_1 src1_sel:DWORD
	v_add3_u32 v11, v11, v21, s34
	v_add3_u32 v10, v10, v24, s34
	v_add3_u32 v19, v26, v19, s34
	v_add3_u32 v0, v27, v0, s34
	v_and_b32_e32 v11, 0xffff0000, v11
	v_and_b32_e32 v10, 0xffff0000, v10
	v_or_b32_sdwa v11, v11, v0 dst_sel:DWORD dst_unused:UNUSED_PAD src0_sel:DWORD src1_sel:WORD_1
	v_or_b32_sdwa v10, v10, v19 dst_sel:DWORD dst_unused:UNUSED_PAD src0_sel:DWORD src1_sel:WORD_1
	ds_write_b128 v64, v[8:11] offset:8448
	v_lshl_add_u64 v[8:9], v[22:23], 0, s[18:19]
	v_lshlrev_b64 v[8:9], 9, v[8:9]
	v_lshl_add_u64 v[8:9], s[14:15], 0, v[8:9]
	v_lshl_add_u64 v[24:25], v[12:13], 1, v[8:9]
	global_load_dwordx4 v[8:11], v[24:25], off
	v_mov_b32_e32 v27, 0
	v_mov_b32_e32 v29, 0
	s_and_saveexec_b64 s[18:19], s[40:41]
	s_cbranch_execz .LBB0_1823
	global_load_ushort v251, v[24:25], off offset:-2

.LBB0_1825:
	s_or_b64 exec, exec, s[18:19]
	s_waitcnt vmcnt(0)
	v_lshlrev_b32_e32 v250, 16, v251
	v_cndmask_b32_e64 v29, v29, v250, s[40:41]
	s_waitcnt vmcnt(0)
	v_lshlrev_b32_e32 v39, 16, v9
	v_and_b32_e32 v40, 0xffff0000, v8
	v_mov_b32_e32 v32, v16
	v_mov_b32_e32 v33, v16
	v_and_b32_e32 v35, 0xffff0000, v9
	v_lshlrev_b32_e32 v38, 16, v8
	v_mov_b32_e32 v42, v40
	v_mov_b32_e32 v43, v39
	v_mov_b32_e32 v24, v17
	v_mov_b32_e32 v25, v17
	v_mov_b32_e32 v8, v38
	v_mov_b32_e32 v9, v40
	v_pk_mul_f32 v[42:43], v[32:33], v[42:43]
	v_mov_b32_e32 v28, v35
	v_mov_b32_e32 v19, v18
	v_mov_b32_e32 v34, v39
	v_pk_fma_f32 v[8:9], v[24:25], v[8:9], v[42:43]
	v_pk_mul_f32 v[28:29], v[16:17], v[28:29]
	v_mov_b32_e32 v21, v20
	v_lshlrev_b32_e32 v41, 16, v10
	v_pk_fma_f32 v[8:9], v[18:19], v[34:35], v[8:9]
	v_pk_fma_f32 v[28:29], v[16:17], v[38:39], v[28:29] op_sel:[0,0,1] op_sel_hi:[1,1,0]
	v_pk_add_f32 v[8:9], v[20:21], v[8:9]
	v_pk_fma_f32 v[28:29], v[18:19], v[40:41], v[28:29]
	v_and_b32_sdwa v34, v8, v208 dst_sel:DWORD dst_unused:UNUSED_PAD src0_sel:WORD_1 src1_sel:DWORD
	v_pk_add_f32 v[28:29], v[20:21], v[28:29]
	v_and_b32_sdwa v26, v9, v208 dst_sel:DWORD dst_unused:UNUSED_PAD src0_sel:WORD_1 src1_sel:DWORD
	v_add3_u32 v8, v8, v34, s34
	v_and_b32_sdwa v34, v28, v208 dst_sel:DWORD dst_unused:UNUSED_PAD src0_sel:WORD_1 src1_sel:DWORD
	v_lshlrev_b32_e32 v37, 16, v11
	v_add3_u32 v9, v9, v26, s34
	v_and_b32_e32 v8, 0xffff0000, v8
	v_and_b32_sdwa v26, v29, v208 dst_sel:DWORD dst_unused:UNUSED_PAD src0_sel:WORD_1 src1_sel:DWORD
	v_add3_u32 v28, v28, v34, s34
	v_and_b32_e32 v11, 0xffff0000, v11
	v_and_b32_e32 v10, 0xffff0000, v10
	v_add3_u32 v26, v29, v26, s34
	v_or_b32_sdwa v8, v28, v8 dst_sel:DWORD dst_unused:UNUSED_PAD src0_sel:WORD_1 src1_sel:DWORD
	v_pk_mov_b32 v[28:29], v[34:35], v[10:11] op_sel:[1,0]
	v_mov_b32_e32 v34, v41
	v_mov_b32_e32 v35, v37
	v_pk_mul_f32 v[32:33], v[32:33], v[34:35]
	v_mov_b32_e32 v40, v11
	v_pk_fma_f32 v[24:25], v[24:25], v[28:29], v[32:33]
	v_and_b32_e32 v26, 0xffff0000, v26
	v_mov_b32_e32 v36, v10
	v_pk_fma_f32 v[24:25], v[18:19], v[10:11], v[24:25]
	v_pk_mul_f32 v[10:11], v[16:17], v[40:41]
	v_or_b32_sdwa v9, v26, v9 dst_sel:DWORD dst_unused:UNUSED_PAD src0_sel:DWORD src1_sel:WORD_1
	v_pk_fma_f32 v[10:11], v[16:17], v[36:37], v[10:11] op_sel:[0,0,1] op_sel_hi:[1,1,0]
	v_mov_b32_e32 v26, v37
	v_pk_fma_f32 v[10:11], v[18:19], v[26:27], v[10:11]
	v_pk_add_f32 v[24:25], v[20:21], v[24:25]
	v_pk_add_f32 v[10:11], v[20:21], v[10:11]
	v_and_b32_sdwa v16, v25, v208 dst_sel:DWORD dst_unused:UNUSED_PAD src0_sel:WORD_1 src1_sel:DWORD
	v_and_b32_sdwa v18, v11, v208 dst_sel:DWORD dst_unused:UNUSED_PAD src0_sel:WORD_1 src1_sel:DWORD
	v_and_b32_sdwa v19, v10, v208 dst_sel:DWORD dst_unused:UNUSED_PAD src0_sel:WORD_1 src1_sel:DWORD
	v_and_b32_sdwa v17, v24, v208 dst_sel:DWORD dst_unused:UNUSED_PAD src0_sel:WORD_1 src1_sel:DWORD
	v_add3_u32 v11, v11, v18, s34
	v_add3_u32 v10, v10, v19, s34
	v_add3_u32 v17, v24, v17, s34
	v_add3_u32 v16, v25, v16, s34
	v_and_b32_e32 v11, 0xffff0000, v11
	v_and_b32_e32 v10, 0xffff0000, v10
	s_add_i32 s20, s8, 0x200
	v_or_b32_sdwa v11, v11, v16 dst_sel:DWORD dst_unused:UNUSED_PAD src0_sel:DWORD src1_sel:WORD_1
	v_or_b32_sdwa v10, v10, v17 dst_sel:DWORD dst_unused:UNUSED_PAD src0_sel:DWORD src1_sel:WORD_1
	s_ashr_i32 s21, s20, 31
	ds_write_b128 v65, v[8:11] offset:8448
	v_lshl_add_u64 v[10:11], v[14:15], 0, s[20:21]
	v_lshl_add_u64 v[2:3], v[2:3], 1, s[14:15]
	v_lshlrev_b64 v[10:11], 9, v[10:11]
	v_sub_u32_e32 v8, 0, v30
	v_lshl_add_u64 v[2:3], v[2:3], 0, v[10:11]
	v_lshl_add_u64 v[10:11], v[22:23], 0, s[20:21]
	v_and_b32_e32 v16, 7, v8
	v_lshl_add_u64 v[8:9], v[12:13], 1, s[14:15]
	v_lshlrev_b64 v[10:11], 9, v[10:11]
	v_lshlrev_b32_e32 v67, 3, v30
	v_lshl_add_u64 v[40:41], v[8:9], 0, v[10:11]
	v_sub_u32_e32 v10, 0x200, v67
	v_ashrrev_i32_e32 v11, 31, v10
	v_lshlrev_b64 v[44:45], 11, v[10:11]
	v_sub_u32_e32 v10, 0x1ff, v67
	s_add_u32 s14, s16, 0x800
	v_ashrrev_i32_e32 v11, 31, v10
	s_addc_u32 s15, s17, 0
	v_lshlrev_b64 v[46:47], 11, v[10:11]
	v_sub_u32_e32 v10, 0x1fe, v67
	v_and_b32_e32 v62, 15, v30
	v_bfe_u32 v0, v30, 4, 2
	s_add_u32 s18, s16, 0x2000
	v_and_b32_e32 v8, 0xffffffc0, v30
	v_ashrrev_i32_e32 v11, 31, v10
	v_lshlrev_b32_e32 v66, 3, v0
	s_addc_u32 s19, s17, 0
	v_lshl_or_b32 v42, v0, 2, v8
	v_or_b32_e32 v0, s4, v62
	v_lshlrev_b64 v[48:49], 11, v[10:11]
	v_sub_u32_e32 v10, 0x1fd, v67
	s_add_u32 s16, s16, 0x3800
	v_readlane_b32 s20, v253, 55
	v_lshlrev_b32_e32 v0, 18, v0
	v_ashrrev_i32_e32 v11, 31, v10
	s_addc_u32 s17, s17, 0
	s_add_i32 s24, s8, s20
	v_lshl_add_u64 v[8:9], s[12:13], 0, v[0:1]
	s_lshl_b64 s[8:9], s[8:9], 9
	v_lshlrev_b64 v[50:51], 11, v[10:11]
	v_sub_u32_e32 v10, 0x1fc, v67
	v_lshl_add_u64 v[8:9], v[8:9], 0, s[8:9]
	v_ashrrev_i32_e32 v11, 31, v10
	v_ashrrev_i32_e32 v43, 31, v42
	v_mul_u32_u24_e32 v69, 0x108, v62
	v_lshlrev_b64 v[52:53], 11, v[10:11]
	v_sub_u32_e32 v10, 0x1fb, v67
	v_lshl_add_u64 v[8:9], v[42:43], 1, v[8:9]
	s_mov_b64 s[8:9], 0xd680000
	v_lshlrev_b32_e32 v12, 1, v69
	v_ashrrev_i32_e32 v11, 31, v10
	v_lshl_add_u64 v[60:61], v[8:9], 0, s[8:9]
	v_and_b32_e32 v8, 48, v30
	s_movk_i32 s4, 0x420
	v_lshlrev_b64 v[54:55], 11, v[10:11]
	v_sub_u32_e32 v10, 0x1fa, v67
	v_add_u32_e32 v43, v8, v12
	v_mad_u32_u24 v8, v16, s4, v8
	v_add_lshl_u32 v9, v16, v62, 1
	v_ashrrev_i32_e32 v11, 31, v10
	v_sub_u32_e32 v8, v8, v9
	v_lshlrev_b32_e32 v9, 1, v30
	v_and_b32_e32 v31, 63, v30
	v_lshlrev_b64 v[56:57], 11, v[10:11]
	v_sub_u32_e32 v10, 0x1f9, v67
	v_and_b32_e32 v9, 0xffffff80, v9
	v_readlane_b32 s21, v253, 56
	v_ashrrev_i32_e32 v11, 31, v10
	v_lshlrev_b32_e32 v0, 11, v31
	v_sub_u32_e32 v8, v8, v9
	s_mov_b32 s25, 0
	v_cmp_gt_i32_e64 s[44:45], 64, v30
	v_lshlrev_b32_e32 v68, 4, v30
	v_cmp_gt_i32_e64 s[46:47], 2, v30
	v_cmp_gt_u32_e64 s[48:49], 32, v31
	v_cmp_lt_i32_e64 s[50:51], 0, v30
	v_cmp_lt_i32_e64 s[52:53], -1, v30
	v_lshlrev_b64 v[58:59], 11, v[10:11]
	v_lshl_add_u32 v70, v42, 1, v12
	v_add_u32_e32 v71, 0x1a0, v8
	s_mov_b64 s[8:9], -1
	s_mov_b64 s[20:21], 0
	v_lshlrev_b32_e32 v0, 2, v0
	s_branch .LBB0_1827

.LBB0_1827:
	s_andn2_b64 vcc, exec, s[20:21]
	s_cbranch_vccnz .LBB0_1837
	global_load_dword v17, v1, s[14:15]
	global_load_dword v16, v1, s[18:19]
	global_load_dword v14, v1, s[16:17]
	global_load_dword v12, v1, s[2:3] offset:2048
	global_load_dwordx4 v[8:11], v[2:3], off
	v_mov_b32_e32 v19, 0
	v_mov_b32_e32 v21, 0
	s_and_saveexec_b64 s[12:13], s[36:37]
	s_cbranch_execz .LBB0_1830
	global_load_ushort v251, v[2:3], off offset:-2

.LBB0_1832:
	s_or_b64 exec, exec, s[12:13]
	s_waitcnt vmcnt(0)
	v_lshlrev_b32_e32 v250, 16, v251
	v_cndmask_b32_e64 v21, v21, v250, s[36:37]
	s_waitcnt vmcnt(0)
	v_lshlrev_b32_e32 v27, 16, v9
	v_and_b32_e32 v28, 0xffff0000, v8
	v_and_b32_e32 v23, 0xffff0000, v9
	v_lshlrev_b32_e32 v26, 16, v8
	v_mov_b32_e32 v30, v28
	v_mov_b32_e32 v31, v27
	v_mov_b32_e32 v8, v26
	v_mov_b32_e32 v9, v28
	v_mov_b32_e32 v18, v17
	v_pk_mul_f32 v[30:31], v[16:17], v[30:31] op_sel_hi:[0,1]
	v_mov_b32_e32 v20, v23
	v_mov_b32_e32 v22, v27
	v_pk_fma_f32 v[8:9], v[18:19], v[8:9], v[30:31] op_sel_hi:[0,1,1]
	v_pk_mul_f32 v[20:21], v[16:17], v[20:21]
	v_lshlrev_b32_e32 v29, 16, v10
	v_pk_fma_f32 v[8:9], v[14:15], v[22:23], v[8:9] op_sel_hi:[0,1,1]
	v_pk_fma_f32 v[20:21], v[16:17], v[26:27], v[20:21] op_sel:[0,0,1] op_sel_hi:[1,1,0]
	v_pk_add_f32 v[8:9], v[12:13], v[8:9] op_sel_hi:[0,1]
	v_pk_fma_f32 v[20:21], v[14:15], v[28:29], v[20:21] op_sel_hi:[0,1,1]
	v_pk_add_f32 v[20:21], v[12:13], v[20:21] op_sel_hi:[0,1]
	v_and_b32_sdwa v13, v9, v208 dst_sel:DWORD dst_unused:UNUSED_PAD src0_sel:WORD_1 src1_sel:DWORD
	v_and_b32_sdwa v15, v8, v208 dst_sel:DWORD dst_unused:UNUSED_PAD src0_sel:WORD_1 src1_sel:DWORD
	v_lshlrev_b32_e32 v25, 16, v11
	v_add3_u32 v9, v9, v13, s34
	v_add3_u32 v8, v8, v15, s34
	v_and_b32_sdwa v13, v21, v208 dst_sel:DWORD dst_unused:UNUSED_PAD src0_sel:WORD_1 src1_sel:DWORD
	v_and_b32_sdwa v15, v20, v208 dst_sel:DWORD dst_unused:UNUSED_PAD src0_sel:WORD_1 src1_sel:DWORD
	v_and_b32_e32 v11, 0xffff0000, v11
	v_and_b32_e32 v10, 0xffff0000, v10
	v_add3_u32 v13, v21, v13, s34
	v_add3_u32 v15, v20, v15, s34
	v_pk_mov_b32 v[20:21], v[22:23], v[10:11] op_sel:[1,0]
	v_mov_b32_e32 v22, v29
	v_mov_b32_e32 v23, v25
	v_pk_mul_f32 v[22:23], v[16:17], v[22:23] op_sel_hi:[0,1]
	v_pk_fma_f32 v[20:21], v[18:19], v[20:21], v[22:23] op_sel_hi:[0,1,1]
	v_mov_b32_e32 v28, v11
	v_mov_b32_e32 v24, v10
	v_pk_fma_f32 v[20:21], v[14:15], v[10:11], v[20:21] op_sel_hi:[0,1,1]
	v_pk_mul_f32 v[10:11], v[16:17], v[28:29]
	v_mov_b32_e32 v18, v25
	v_pk_fma_f32 v[10:11], v[16:17], v[24:25], v[10:11] op_sel:[0,0,1] op_sel_hi:[1,1,0]
	v_and_b32_e32 v13, 0xffff0000, v13
	v_pk_fma_f32 v[10:11], v[14:15], v[18:19], v[10:11] op_sel_hi:[0,1,1]
	v_pk_add_f32 v[10:11], v[12:13], v[10:11] op_sel_hi:[0,1]
	v_and_b32_e32 v8, 0xffff0000, v8
	v_pk_add_f32 v[20:21], v[12:13], v[20:21] op_sel_hi:[0,1]
	v_and_b32_sdwa v18, v11, v208 dst_sel:DWORD dst_unused:UNUSED_PAD src0_sel:WORD_1 src1_sel:DWORD
	v_and_b32_sdwa v19, v10, v208 dst_sel:DWORD dst_unused:UNUSED_PAD src0_sel:WORD_1 src1_sel:DWORD
	v_or_b32_sdwa v9, v13, v9 dst_sel:DWORD dst_unused:UNUSED_PAD src0_sel:DWORD src1_sel:WORD_1
	v_or_b32_sdwa v8, v15, v8 dst_sel:DWORD dst_unused:UNUSED_PAD src0_sel:WORD_1 src1_sel:DWORD
	v_and_b32_sdwa v13, v21, v208 dst_sel:DWORD dst_unused:UNUSED_PAD src0_sel:WORD_1 src1_sel:DWORD
	v_and_b32_sdwa v15, v20, v208 dst_sel:DWORD dst_unused:UNUSED_PAD src0_sel:WORD_1 src1_sel:DWORD
	v_add3_u32 v11, v11, v18, s34
	v_add3_u32 v10, v10, v19, s34
	v_add3_u32 v15, v20, v15, s34
	v_add3_u32 v13, v21, v13, s34
	v_and_b32_e32 v11, 0xffff0000, v11
	v_and_b32_e32 v10, 0xffff0000, v10
	v_or_b32_sdwa v11, v11, v13 dst_sel:DWORD dst_unused:UNUSED_PAD src0_sel:DWORD src1_sel:WORD_1
	v_or_b32_sdwa v10, v10, v15 dst_sel:DWORD dst_unused:UNUSED_PAD src0_sel:DWORD src1_sel:WORD_1
	ds_write_b128 v64, v[8:11] offset:16896
	global_load_dwordx4 v[8:11], v[40:41], off
	v_mov_b32_e32 v19, 0
	v_mov_b32_e32 v21, 0
	s_and_saveexec_b64 s[12:13], s[40:41]
	s_cbranch_execz .LBB0_1834
	global_load_ushort v251, v[40:41], off offset:-2

.LBB0_1836:
	s_or_b64 exec, exec, s[12:13]
	s_waitcnt vmcnt(0)
	v_lshlrev_b32_e32 v250, 16, v251
	v_cndmask_b32_e64 v21, v21, v250, s[40:41]
	s_waitcnt vmcnt(0)
	v_lshlrev_b32_e32 v31, 16, v9
	v_and_b32_e32 v32, 0xffff0000, v8
	v_mov_b32_e32 v24, v16
	v_mov_b32_e32 v25, v16
	v_and_b32_e32 v27, 0xffff0000, v9
	v_lshlrev_b32_e32 v30, 16, v8
	v_mov_b32_e32 v34, v32
	v_mov_b32_e32 v35, v31
	v_mov_b32_e32 v22, v17
	v_mov_b32_e32 v23, v17
	v_mov_b32_e32 v8, v30
	v_mov_b32_e32 v9, v32
	v_pk_mul_f32 v[34:35], v[24:25], v[34:35]
	v_mov_b32_e32 v20, v27
	v_mov_b32_e32 v15, v14
	v_mov_b32_e32 v26, v31
	v_pk_fma_f32 v[8:9], v[22:23], v[8:9], v[34:35]
	v_pk_mul_f32 v[20:21], v[16:17], v[20:21]
	v_mov_b32_e32 v13, v12
	v_lshlrev_b32_e32 v33, 16, v10
	v_pk_fma_f32 v[8:9], v[14:15], v[26:27], v[8:9]
	v_pk_fma_f32 v[20:21], v[16:17], v[30:31], v[20:21] op_sel:[0,0,1] op_sel_hi:[1,1,0]
	v_pk_add_f32 v[8:9], v[12:13], v[8:9]
	v_pk_fma_f32 v[20:21], v[14:15], v[32:33], v[20:21]
	v_and_b32_sdwa v26, v8, v208 dst_sel:DWORD dst_unused:UNUSED_PAD src0_sel:WORD_1 src1_sel:DWORD
	v_pk_add_f32 v[20:21], v[12:13], v[20:21]
	v_and_b32_sdwa v18, v9, v208 dst_sel:DWORD dst_unused:UNUSED_PAD src0_sel:WORD_1 src1_sel:DWORD
	v_add3_u32 v8, v8, v26, s34
	v_and_b32_sdwa v26, v20, v208 dst_sel:DWORD dst_unused:UNUSED_PAD src0_sel:WORD_1 src1_sel:DWORD
	v_lshlrev_b32_e32 v29, 16, v11
	v_add3_u32 v9, v9, v18, s34
	v_and_b32_e32 v8, 0xffff0000, v8
	v_and_b32_sdwa v18, v21, v208 dst_sel:DWORD dst_unused:UNUSED_PAD src0_sel:WORD_1 src1_sel:DWORD
	v_add3_u32 v20, v20, v26, s34
	v_and_b32_e32 v11, 0xffff0000, v11
	v_and_b32_e32 v10, 0xffff0000, v10
	v_add3_u32 v18, v21, v18, s34
	v_or_b32_sdwa v8, v20, v8 dst_sel:DWORD dst_unused:UNUSED_PAD src0_sel:WORD_1 src1_sel:DWORD
	v_pk_mov_b32 v[20:21], v[26:27], v[10:11] op_sel:[1,0]
	v_mov_b32_e32 v26, v33
	v_mov_b32_e32 v27, v29
	v_pk_mul_f32 v[24:25], v[24:25], v[26:27]
	v_mov_b32_e32 v32, v11
	v_pk_fma_f32 v[20:21], v[22:23], v[20:21], v[24:25]
	v_and_b32_e32 v18, 0xffff0000, v18
	v_mov_b32_e32 v28, v10
	v_pk_fma_f32 v[20:21], v[14:15], v[10:11], v[20:21]
	v_pk_mul_f32 v[10:11], v[16:17], v[32:33]
	v_or_b32_sdwa v9, v18, v9 dst_sel:DWORD dst_unused:UNUSED_PAD src0_sel:DWORD src1_sel:WORD_1
	v_pk_fma_f32 v[10:11], v[16:17], v[28:29], v[10:11] op_sel:[0,0,1] op_sel_hi:[1,1,0]
	v_mov_b32_e32 v18, v29
	v_pk_fma_f32 v[10:11], v[14:15], v[18:19], v[10:11]
	v_pk_add_f32 v[20:21], v[12:13], v[20:21]
	v_pk_add_f32 v[10:11], v[12:13], v[10:11]
	v_and_b32_sdwa v12, v21, v208 dst_sel:DWORD dst_unused:UNUSED_PAD src0_sel:WORD_1 src1_sel:DWORD
	v_and_b32_sdwa v14, v11, v208 dst_sel:DWORD dst_unused:UNUSED_PAD src0_sel:WORD_1 src1_sel:DWORD
	v_and_b32_sdwa v15, v10, v208 dst_sel:DWORD dst_unused:UNUSED_PAD src0_sel:WORD_1 src1_sel:DWORD
	v_and_b32_sdwa v13, v20, v208 dst_sel:DWORD dst_unused:UNUSED_PAD src0_sel:WORD_1 src1_sel:DWORD
	v_add3_u32 v11, v11, v14, s34
	v_add3_u32 v10, v10, v15, s34
	v_add3_u32 v13, v20, v13, s34
	v_add3_u32 v12, v21, v12, s34
	v_and_b32_e32 v11, 0xffff0000, v11
	v_and_b32_e32 v10, 0xffff0000, v10
	v_or_b32_sdwa v11, v11, v12 dst_sel:DWORD dst_unused:UNUSED_PAD src0_sel:DWORD src1_sel:WORD_1
	v_or_b32_sdwa v10, v10, v13 dst_sel:DWORD dst_unused:UNUSED_PAD src0_sel:DWORD src1_sel:WORD_1
	ds_write_b128 v65, v[8:11] offset:16896
